# GEMM accumulator zero-init via 7 zero-operand 32x32x16 MFMAs + 15 v_mov instead of 127 v_mov (4 GEMM phases)
# baseline (speedup 1.0000x reference)
;     __device__ __forceinline__ const char* Ap(int part) const { return (const char*)A0 + (long)(part == 1) * ((const char*)A1 - (const char*)A0) + (long)(part == 2) * ((const char*)A2 - (const char*)A0); }
;     __device__ __forceinline__ const char* Bp(int part) const { return (const char*)B0 + (long)(part == 1) * ((const char*)B1 - (const char*)B0) + (long)(part == 2) * ((const char*)B2 - (const char*)B0); }
; template <class Epi, bool GS = false>
; __device__ __forceinline__ void gemm_phase(LAS unsigned char* lds, const Gemm g, const StaticOrder& S, const Epi& E, const int tid) {
;     ...
;         const char* nA = has_next ? g.Ap(nxt.part) + (size_t)nxt.pm * tstepA : cA; const char* nB = has_next ? g.Bp(nxt.part) + (size_t)nxt.pn * tstepB : cB;
;         const int nt = g.Kp(cur.part) / BK;
;         const int seg = (GS && cur.part == 0) ? 8 : nt;
;         for (int tg = 0; tg < nt; tg += seg) {
;         for (int t = tg; t < tg + seg; t += 2) {
;             const bool last = (t == nt - 2);
;             const char* a1 = cA + (size_t)(t + 1) * kstep;
;             const char* a2 = last ? nA : cA + (size_t)(t + 2) * kstep; const char* b2 = last ? nB : cB + (size_t)(t + 2) * kstep;
;             const char* a3 = a2 + kstep; const char* b3 = b2 + kstep;
;     ...
; #pragma unroll
;         for (int a = 0; a < 2; ++a)
; #pragma unroll
;             for (int b = 0; b < 2; ++b)
; #pragma unroll
;                 for (int m = 0; m < 4; ++m)
; #pragma unroll
;                     for (int n = 0; n < 2; ++n) acc[a][b][m][n] = (f32x4){0.f, 0.f, 0.f, 0.f};
.LBB0_204:
	s_ashr_i32 s21, s20, 31
	s_lshl_b64 s[22:23], s[20:21], 19
	s_add_u32 s22, s12, s22
	s_addc_u32 s23, s13, s23
	s_and_b64 s[42:43], s[4:5], exec
	s_cselect_b32 s21, s23, s45
	s_cselect_b32 s55, s22, s44
	s_ashr_i32 s17, s16, 31
	s_lshl_b64 s[42:43], s[16:17], 19
	v_readlane_b32 s17, v255, 20
	s_add_u32 s42, s17, s42
	v_readlane_b32 s17, v255, 22
	s_addc_u32 s43, s17, s43
	s_and_b64 s[48:49], s[4:5], exec
	s_cselect_b32 s17, s43, s47
	s_cselect_b32 s56, s42, s46
	s_add_u32 s44, s44, 0x40080
	s_addc_u32 s45, s45, 0
	s_add_u32 s57, s46, 0x100
	v_mov_b32_e32 v2, 0
	s_addc_u32 s58, s47, 0
	s_mov_b32 s59, -2
	s_waitcnt vmcnt(0)
	v_mov_b32_e32 v3, v2
	v_mov_b32_e32 v4, v2
	v_mov_b32_e32 v5, v2
	v_mov_b32_e32 v6, v2
	v_mov_b32_e32 v7, v2
	v_mov_b32_e32 v8, v2
	v_mov_b32_e32 v9, v2
	v_mov_b32_e32 v10, v2
	v_mov_b32_e32 v11, v2
	v_mov_b32_e32 v12, v2
	v_mov_b32_e32 v13, v2
	v_mov_b32_e32 v14, v2
	v_mov_b32_e32 v15, v2
	v_mov_b32_e32 v16, v2
	v_mov_b32_e32 v17, v2
	v_mfma_f32_32x32x16_bf16 v[18:33], v[2:5], v[2:5], 0
	v_mfma_f32_32x32x16_bf16 v[34:49], v[2:5], v[2:5], 0
	v_mfma_f32_32x32x16_bf16 v[50:65], v[2:5], v[2:5], 0
	v_mfma_f32_32x32x16_bf16 v[66:81], v[2:5], v[2:5], 0
	v_mfma_f32_32x32x16_bf16 v[82:97], v[2:5], v[2:5], 0
	v_mfma_f32_32x32x16_bf16 v[98:113], v[2:5], v[2:5], 0
	v_mfma_f32_32x32x16_bf16 v[114:129], v[2:5], v[2:5], 0

;     __device__ __forceinline__ const char* Ap(int part) const { return (const char*)A0 + (long)(part == 1) * ((const char*)A1 - (const char*)A0) + (long)(part == 2) * ((const char*)A2 - (const char*)A0); }
;     __device__ __forceinline__ const char* Bp(int part) const { return (const char*)B0 + (long)(part == 1) * ((const char*)B1 - (const char*)B0) + (long)(part == 2) * ((const char*)B2 - (const char*)B0); }
; template <class Epi, bool GS = false>
; __device__ __forceinline__ void gemm_phase(LAS unsigned char* lds, const Gemm g, const StaticOrder& S, const Epi& E, const int tid) {
;     ...
;         const char* nA = has_next ? g.Ap(nxt.part) + (size_t)nxt.pm * tstepA : cA; const char* nB = has_next ? g.Bp(nxt.part) + (size_t)nxt.pn * tstepB : cB;
;         const int nt = g.Kp(cur.part) / BK;
;         const int seg = (GS && cur.part == 0) ? 8 : nt;
;         for (int tg = 0; tg < nt; tg += seg) {
;         for (int t = tg; t < tg + seg; t += 2) {
;             const bool last = (t == nt - 2);
;             const char* a1 = cA + (size_t)(t + 1) * kstep;
;             const char* a2 = last ? nA : cA + (size_t)(t + 2) * kstep; const char* b2 = last ? nB : cB + (size_t)(t + 2) * kstep;
;             const char* a3 = a2 + kstep; const char* b3 = b2 + kstep;
;     ...
; #pragma unroll
;         for (int a = 0; a < 2; ++a)
; #pragma unroll
;             for (int b = 0; b < 2; ++b)
; #pragma unroll
;                 for (int m = 0; m < 4; ++m)
; #pragma unroll
;                     for (int n = 0; n < 2; ++n) acc[a][b][m][n] = (f32x4){0.f, 0.f, 0.f, 0.f};
.LBB0_780:
	s_ashr_i32 s17, s16, 31
	s_lshl_b64 s[20:21], s[16:17], 19
	s_add_u32 s20, s12, s20
	s_addc_u32 s21, s13, s21
	s_and_b64 s[22:23], s[4:5], exec
	s_cselect_b32 s17, s21, s43
	s_cselect_b32 s39, s20, s42
	s_ashr_i32 s15, s14, 31
	s_lshl_b64 s[22:23], s[14:15], 19
	v_readlane_b32 s15, v255, 21
	s_add_u32 s22, s15, s22
	v_readlane_b32 s15, v255, 23
	s_addc_u32 s23, s15, s23
	s_and_b64 s[46:47], s[4:5], exec
	s_cselect_b32 s15, s23, s45
	s_cselect_b32 s54, s22, s44
	s_add_u32 s42, s42, 0x40080
	s_addc_u32 s43, s43, 0
	s_add_u32 s55, s44, 0x100
	v_mov_b32_e32 v2, 0
	s_addc_u32 s56, s45, 0
	s_mov_b32 s57, -2
	s_waitcnt vmcnt(0)
	v_mov_b32_e32 v3, v2
	v_mov_b32_e32 v4, v2
	v_mov_b32_e32 v5, v2
	v_mov_b32_e32 v6, v2
	v_mov_b32_e32 v7, v2
	v_mov_b32_e32 v8, v2
	v_mov_b32_e32 v9, v2
	v_mov_b32_e32 v10, v2
	v_mov_b32_e32 v11, v2
	v_mov_b32_e32 v12, v2
	v_mov_b32_e32 v13, v2
	v_mov_b32_e32 v14, v2
	v_mov_b32_e32 v15, v2
	v_mov_b32_e32 v16, v2
	v_mov_b32_e32 v17, v2
	v_mfma_f32_32x32x16_bf16 v[18:33], v[2:5], v[2:5], 0
	v_mfma_f32_32x32x16_bf16 v[34:49], v[2:5], v[2:5], 0
	v_mfma_f32_32x32x16_bf16 v[50:65], v[2:5], v[2:5], 0
	v_mfma_f32_32x32x16_bf16 v[66:81], v[2:5], v[2:5], 0
	v_mfma_f32_32x32x16_bf16 v[82:97], v[2:5], v[2:5], 0
	v_mfma_f32_32x32x16_bf16 v[98:113], v[2:5], v[2:5], 0
	v_mfma_f32_32x32x16_bf16 v[114:129], v[2:5], v[2:5], 0

;     __device__ __forceinline__ const char* Ap(int part) const { return (const char*)A0 + (long)(part == 1) * ((const char*)A1 - (const char*)A0) + (long)(part == 2) * ((const char*)A2 - (const char*)A0); }
;     __device__ __forceinline__ const char* Bp(int part) const { return (const char*)B0 + (long)(part == 1) * ((const char*)B1 - (const char*)B0) + (long)(part == 2) * ((const char*)B2 - (const char*)B0); }
; template <class Epi, bool GS = false>
; __device__ __forceinline__ void gemm_phase(LAS unsigned char* lds, const Gemm g, const StaticOrder& S, const Epi& E, const int tid) {
;     ...
;         const char* nA = has_next ? g.Ap(nxt.part) + (size_t)nxt.pm * tstepA : cA; const char* nB = has_next ? g.Bp(nxt.part) + (size_t)nxt.pn * tstepB : cB;
;         const int nt = g.Kp(cur.part) / BK;
;         const int seg = (GS && cur.part == 0) ? 8 : nt;
;         for (int tg = 0; tg < nt; tg += seg) {
;         for (int t = tg; t < tg + seg; t += 2) {
;             const bool last = (t == nt - 2);
;             const char* a1 = cA + (size_t)(t + 1) * kstep;
;             const char* a2 = last ? nA : cA + (size_t)(t + 2) * kstep; const char* b2 = last ? nB : cB + (size_t)(t + 2) * kstep;
;             const char* a3 = a2 + kstep; const char* b3 = b2 + kstep;
;     ...
; #pragma unroll
;         for (int a = 0; a < 2; ++a)
; #pragma unroll
;             for (int b = 0; b < 2; ++b)
; #pragma unroll
;                 for (int m = 0; m < 4; ++m)
; #pragma unroll
;                     for (int n = 0; n < 2; ++n) acc[a][b][m][n] = (f32x4){0.f, 0.f, 0.f, 0.f};
.LBB0_920:
	s_ashr_i32 s15, s14, 31
	s_lshl_b64 s[16:17], s[14:15], 19
	s_add_u32 s16, s12, s16
	s_addc_u32 s17, s13, s17
	s_and_b64 s[20:21], s[38:39], exec
	s_cselect_b32 s15, s17, s23
	s_cselect_b32 s47, s16, s22
	s_ashr_i32 s9, s8, 31
	s_lshl_b64 s[20:21], s[8:9], 19
	s_add_u32 s20, s2, s20
	s_addc_u32 s21, s3, s21
	s_and_b64 s[34:35], s[38:39], exec
	s_cselect_b32 s9, s21, s31
	s_cselect_b32 s48, s20, s30
	s_add_u32 s22, s22, 0x40080
	s_addc_u32 s23, s23, 0
	s_add_u32 s49, s30, 0x100
	v_mov_b32_e32 v2, 0
	s_addc_u32 s50, s31, 0
	s_mov_b32 s51, -2
	v_mov_b32_e32 v3, v2
	v_mov_b32_e32 v4, v2
	v_mov_b32_e32 v5, v2
	v_mov_b32_e32 v6, v2
	v_mov_b32_e32 v7, v2
	v_mov_b32_e32 v8, v2
	v_mov_b32_e32 v9, v2
	v_mov_b32_e32 v10, v2
	v_mov_b32_e32 v11, v2
	v_mov_b32_e32 v12, v2
	v_mov_b32_e32 v13, v2
	v_mov_b32_e32 v14, v2
	v_mov_b32_e32 v15, v2
	v_mov_b32_e32 v16, v2
	v_mov_b32_e32 v17, v2
	v_mfma_f32_32x32x16_bf16 v[18:33], v[2:5], v[2:5], 0
	v_mfma_f32_32x32x16_bf16 v[34:49], v[2:5], v[2:5], 0
	v_mfma_f32_32x32x16_bf16 v[50:65], v[2:5], v[2:5], 0
	v_mfma_f32_32x32x16_bf16 v[66:81], v[2:5], v[2:5], 0
	v_mfma_f32_32x32x16_bf16 v[82:97], v[2:5], v[2:5], 0
	v_mfma_f32_32x32x16_bf16 v[98:113], v[2:5], v[2:5], 0
	v_mfma_f32_32x32x16_bf16 v[114:129], v[2:5], v[2:5], 0

; template <class Epi, bool GS = false>
; __device__ __forceinline__ void gemm_phase(LAS unsigned char* lds, const Gemm g, const StaticOrder& S, const Epi& E, const int tid) {
;     ...
; #pragma unroll
;         for (int a = 0; a < 2; ++a)
; #pragma unroll
;             for (int b = 0; b < 2; ++b)
; #pragma unroll
;                 for (int m = 0; m < 4; ++m)
; #pragma unroll
;                     for (int n = 0; n < 2; ++n) acc[a][b][m][n] = (f32x4){0.f, 0.f, 0.f, 0.f};
.LBB0_992:
	s_add_u32 s50, s22, 0x100
	v_mov_b32_e32 v2, 0
	s_addc_u32 s51, s23, 0
	s_mov_b32 s52, -2
	v_mov_b32_e32 v3, v2
	v_mov_b32_e32 v4, v2
	v_mov_b32_e32 v5, v2
	v_mov_b32_e32 v6, v2
	v_mov_b32_e32 v7, v2
	v_mov_b32_e32 v8, v2
	v_mov_b32_e32 v9, v2
	v_mov_b32_e32 v10, v2
	v_mov_b32_e32 v11, v2
	v_mov_b32_e32 v12, v2
	v_mov_b32_e32 v13, v2
	v_mov_b32_e32 v14, v2
	v_mov_b32_e32 v15, v2
	v_mov_b32_e32 v16, v2
	v_mov_b32_e32 v17, v2
	v_mfma_f32_32x32x16_bf16 v[18:33], v[2:5], v[2:5], 0
	v_mfma_f32_32x32x16_bf16 v[34:49], v[2:5], v[2:5], 0
	v_mfma_f32_32x32x16_bf16 v[50:65], v[2:5], v[2:5], 0
	v_mfma_f32_32x32x16_bf16 v[66:81], v[2:5], v[2:5], 0
	v_mfma_f32_32x32x16_bf16 v[82:97], v[2:5], v[2:5], 0
	v_mfma_f32_32x32x16_bf16 v[98:113], v[2:5], v[2:5], 0
	v_mfma_f32_32x32x16_bf16 v[114:129], v[2:5], v[2:5], 0
